# stack11: stack10 + acquire invalidate issued right after the barrier arrival atomic (overlaps the poll)
# speedup vs baseline: 1.0447x; 1.0079x over previous
; DI void grid_barrier(unsigned* bar, unsigned k) {
;     ...
;         const unsigned old = __hip_atomic_fetch_add(bar + 64 * (1 + j), 1u, __ATOMIC_RELAXED, __HIP_MEMORY_SCOPE_AGENT);
;         if (old + 1u == k * nsub) __hip_atomic_fetch_add(bar, 1u, __ATOMIC_RELAXED, __HIP_MEMORY_SCOPE_AGENT);
.LBB0_377:
	s_or_b64 exec, exec, s[8:9]
	buffer_inv sc1
	v_readlane_b32 s6, v253, 40
	s_waitcnt lgkmcnt(0)
	s_add_i32 s6, s10, s6
	s_lshr_b32 s6, s6, 3
	s_waitcnt vmcnt(1)
	v_readfirstlane_b32 s7, v1
	s_mul_i32 s6, s6, s93
	s_nop 0
	v_add3_u32 v0, s7, v0, 1
	v_cmp_eq_u32_e32 vcc, s6, v0
	s_and_saveexec_b64 s[6:7], vcc
	s_cbranch_execz .LBB0_380
	s_mov_b64 s[8:9], exec
	v_mbcnt_lo_u32_b32 v0, s8, 0
	v_mbcnt_hi_u32_b32 v0, s9, v0
	v_cmp_eq_u32_e32 vcc, 0, v0
	s_and_b64 s[34:35], exec, vcc
	s_mov_b64 exec, s[34:35]
	s_cbranch_execz .LBB0_380
	s_bcnt1_i32_b64 s8, s[8:9]
	v_mov_b32_e32 v0, s8
	global_atomic_add v193, v0, s[80:81]

; DI void grid_barrier(unsigned* bar, unsigned k) {
;     ...
;         __builtin_amdgcn_fence(__ATOMIC_ACQUIRE, "agent");
;         asm volatile("s_waitcnt vmcnt(0)" ::: "memory");
.LBB0_431:
	s_nop 0
	s_waitcnt vmcnt(0)
